# P5 epilogue rewritten: batched x loads, one ssq+final_g load, wave-private LDS transpose so global loads/stores cover full 128B lines
# speedup vs baseline: 1.0240x; 1.0240x over previous
.LBB0_488:
	v_lshl_add_u32 v140, s8, 8, v162
	v_lshl_or_b32 v143, s42, 8, v164
	v_lshlrev_b32_e32 v141, 2, v140
	v_and_b32_e32 v173, 15, v168
	v_sub_u32_e32 v142, v140, v173
	v_lshrrev_b32_e32 v172, 3, v168
	v_add_u32_e32 v142, v142, v172
	v_lshlrev_b32_e32 v142, 12, v142
	v_mul_u32_u24_e32 v171, 144, v173
	v_mul_u32_u24_e32 v172, 144, v172
	v_lshrrev_b32_e32 v173, 4, v168
	v_lshl_add_u32 v171, v173, 4, v171
	v_lshlrev_b32_e32 v173, 2, v173
	v_sub_u32_e32 v144, v143, v173
	v_lshl_add_u32 v142, v144, 2, v142
	v_and_b32_e32 v173, 7, v168
	v_lshlrev_b32_e32 v173, 4, v173
	v_add_u32_e32 v142, v142, v173
	v_add_u32_e32 v172, v172, v173
	v_lshrrev_b32_e32 v173, 6, v162
	v_lshrrev_b32_e32 v144, 5, v164
	v_lshl_add_u32 v173, v173, 2, v144
	v_mul_u32_u24_e32 v173, 2304, v173
	v_add_u32_e32 v173, 0x20000, v173
	v_add_u32_e32 v171, v171, v173
	v_add_u32_e32 v172, v172, v173
	v_lshlrev_b32_e32 v143, 2, v143
	v_xor_b32_e32 v144, 16, v168
	v_xor_b32_e32 v145, 32, v168
	v_lshlrev_b32_e32 v144, 2, v144
	v_lshlrev_b32_e32 v145, 2, v145
	s_add_u32 s100, s16, 0x0
	s_addc_u32 s101, s17, 0
	s_add_u32 s44, s16, 0x8000
	s_addc_u32 s45, s17, 0
	global_load_dwordx4 v[176:179], v142, s[100:101] nt
	global_load_dwordx4 v[180:183], v142, s[44:45] nt
	global_load_dwordx4 v[184:187], v142, s[100:101] offset:512 nt
	global_load_dwordx4 v[188:191], v142, s[44:45] offset:512 nt
	s_add_u32 s100, s16, 0x10000
	s_addc_u32 s101, s17, 0
	s_add_u32 s44, s16, 0x18000
	s_addc_u32 s45, s17, 0
	global_load_dwordx4 v[192:195], v142, s[100:101] nt
	global_load_dwordx4 v[196:199], v142, s[44:45] nt
	global_load_dwordx4 v[200:203], v142, s[100:101] offset:512 nt
	global_load_dwordx4 v[204:207], v142, s[44:45] offset:512 nt
	s_add_u32 s100, s16, 0x20000
	s_addc_u32 s101, s17, 0
	s_add_u32 s44, s16, 0x28000
	s_addc_u32 s45, s17, 0
	global_load_dwordx4 v[208:211], v142, s[100:101] nt
	global_load_dwordx4 v[212:215], v142, s[44:45] nt
	global_load_dwordx4 v[216:219], v142, s[100:101] offset:512 nt
	global_load_dwordx4 v[220:223], v142, s[44:45] offset:512 nt
	s_add_u32 s100, s16, 0x30000
	s_addc_u32 s101, s17, 0
	s_add_u32 s44, s16, 0x38000
	s_addc_u32 s45, s17, 0
	global_load_dwordx4 v[224:227], v142, s[100:101] nt
	global_load_dwordx4 v[228:231], v142, s[44:45] nt
	global_load_dwordx4 v[232:235], v142, s[100:101] offset:512 nt
	global_load_dwordx4 v[236:239], v142, s[44:45] offset:512 nt
	s_add_u32 s100, s16, 0x80000
	s_addc_u32 s101, s17, 0
	s_add_u32 s44, s16, 0x88000
	s_addc_u32 s45, s17, 0
	global_load_dwordx4 v[240:243], v142, s[100:101] nt
	global_load_dwordx4 v[244:247], v142, s[44:45] nt
	global_load_dwordx4 v[248:251], v142, s[100:101] offset:512 nt
	global_load_dwordx4 v[252:255], v142, s[44:45] offset:512 nt
	s_waitcnt vmcnt(16)
	ds_write_b128 v172, v[176:179]
	ds_write_b128 v172, v[180:183] offset:1152
	ds_read_b128 v[176:179], v171
	ds_read_b128 v[180:183], v171 offset:64
	ds_write_b128 v172, v[184:187]
	ds_write_b128 v172, v[188:191] offset:1152
	ds_read_b128 v[184:187], v171
	ds_read_b128 v[188:191], v171 offset:64
	s_waitcnt lgkmcnt(0)
	v_pk_add_f32 v[124:125], v[124:125], v[176:177]
	v_pk_add_f32 v[126:127], v[126:127], v[178:179]
	v_pk_add_f32 v[120:121], v[120:121], v[180:181]
	v_pk_add_f32 v[122:123], v[122:123], v[182:183]
	v_pk_add_f32 v[116:117], v[116:117], v[184:185]
	v_pk_add_f32 v[118:119], v[118:119], v[186:187]
	v_pk_add_f32 v[112:113], v[112:113], v[188:189]
	v_pk_add_f32 v[114:115], v[114:115], v[190:191]
	v_mul_f32_e32 v176, v125, v125
	v_mul_f32_e32 v177, v127, v127
	v_mul_f32_e32 v178, v121, v121
	v_mul_f32_e32 v179, v123, v123
	v_mul_f32_e32 v180, v117, v117
	v_mul_f32_e32 v181, v119, v119
	v_mul_f32_e32 v182, v113, v113
	v_mul_f32_e32 v183, v115, v115
	v_fmac_f32_e32 v176, v124, v124
	v_fmac_f32_e32 v177, v126, v126
	v_fmac_f32_e32 v178, v120, v120
	v_fmac_f32_e32 v179, v122, v122
	v_fmac_f32_e32 v180, v116, v116
	v_fmac_f32_e32 v181, v118, v118
	v_fmac_f32_e32 v182, v112, v112
	v_fmac_f32_e32 v183, v114, v114
	v_add_f32_e32 v176, v176, v177
	v_add_f32_e32 v178, v178, v179
	v_add_f32_e32 v180, v180, v181
	v_add_f32_e32 v176, v176, v178
	v_add_f32_e32 v176, v176, v180
	v_add_f32_e32 v182, v182, v183
	v_add_f32_e32 v146, v176, v182
	ds_bpermute_b32 v154, v144, v146
	s_add_u32 s100, s16, 0x90000
	s_addc_u32 s101, s17, 0
	s_add_u32 s44, s16, 0x98000
	s_addc_u32 s45, s17, 0
	global_load_dwordx4 v[176:179], v142, s[100:101] nt
	global_load_dwordx4 v[180:183], v142, s[44:45] nt
	global_load_dwordx4 v[184:187], v142, s[100:101] offset:512 nt
	global_load_dwordx4 v[188:191], v142, s[44:45] offset:512 nt
	s_waitcnt vmcnt(16)
	ds_write_b128 v172, v[192:195]
	ds_write_b128 v172, v[196:199] offset:1152
	ds_read_b128 v[192:195], v171
	ds_read_b128 v[196:199], v171 offset:64
	ds_write_b128 v172, v[200:203]
	ds_write_b128 v172, v[204:207] offset:1152
	ds_read_b128 v[200:203], v171
	ds_read_b128 v[204:207], v171 offset:64
	s_waitcnt lgkmcnt(0)
	v_pk_add_f32 v[108:109], v[108:109], v[192:193]
	v_pk_add_f32 v[110:111], v[110:111], v[194:195]
	v_pk_add_f32 v[104:105], v[104:105], v[196:197]
	v_pk_add_f32 v[106:107], v[106:107], v[198:199]
	v_pk_add_f32 v[100:101], v[100:101], v[200:201]
	v_pk_add_f32 v[102:103], v[102:103], v[202:203]
	v_pk_add_f32 v[96:97], v[96:97], v[204:205]
	v_pk_add_f32 v[98:99], v[98:99], v[206:207]
	v_mul_f32_e32 v192, v109, v109
	v_mul_f32_e32 v193, v111, v111
	v_mul_f32_e32 v194, v105, v105
	v_mul_f32_e32 v195, v107, v107
	v_mul_f32_e32 v196, v101, v101
	v_mul_f32_e32 v197, v103, v103
	v_mul_f32_e32 v198, v97, v97
	v_mul_f32_e32 v199, v99, v99
	v_fmac_f32_e32 v192, v108, v108
	v_fmac_f32_e32 v193, v110, v110
	v_fmac_f32_e32 v194, v104, v104
	v_fmac_f32_e32 v195, v106, v106
	v_fmac_f32_e32 v196, v100, v100
	v_fmac_f32_e32 v197, v102, v102
	v_fmac_f32_e32 v198, v96, v96
	v_fmac_f32_e32 v199, v98, v98
	v_add_f32_e32 v192, v192, v193
	v_add_f32_e32 v194, v194, v195
	v_add_f32_e32 v196, v196, v197
	v_add_f32_e32 v192, v192, v194
	v_add_f32_e32 v192, v192, v196
	v_add_f32_e32 v198, v198, v199
	v_add_f32_e32 v147, v192, v198
	ds_bpermute_b32 v155, v144, v147
	s_add_u32 s100, s16, 0xa0000
	s_addc_u32 s101, s17, 0
	s_add_u32 s44, s16, 0xa8000
	s_addc_u32 s45, s17, 0
	global_load_dwordx4 v[192:195], v142, s[100:101] nt
	global_load_dwordx4 v[196:199], v142, s[44:45] nt
	global_load_dwordx4 v[200:203], v142, s[100:101] offset:512 nt
	global_load_dwordx4 v[204:207], v142, s[44:45] offset:512 nt
	s_waitcnt vmcnt(16)
	ds_write_b128 v172, v[208:211]
	ds_write_b128 v172, v[212:215] offset:1152
	ds_read_b128 v[208:211], v171
	ds_read_b128 v[212:215], v171 offset:64
	ds_write_b128 v172, v[216:219]
	ds_write_b128 v172, v[220:223] offset:1152
	ds_read_b128 v[216:219], v171
	ds_read_b128 v[220:223], v171 offset:64
	s_waitcnt lgkmcnt(0)
	v_pk_add_f32 v[92:93], v[92:93], v[208:209]
	v_pk_add_f32 v[94:95], v[94:95], v[210:211]
	v_pk_add_f32 v[88:89], v[88:89], v[212:213]
	v_pk_add_f32 v[90:91], v[90:91], v[214:215]
	v_pk_add_f32 v[84:85], v[84:85], v[216:217]
	v_pk_add_f32 v[86:87], v[86:87], v[218:219]
	v_pk_add_f32 v[80:81], v[80:81], v[220:221]
	v_pk_add_f32 v[82:83], v[82:83], v[222:223]
	v_mul_f32_e32 v208, v93, v93
	v_mul_f32_e32 v209, v95, v95
	v_mul_f32_e32 v210, v89, v89
	v_mul_f32_e32 v211, v91, v91
	v_mul_f32_e32 v212, v85, v85
	v_mul_f32_e32 v213, v87, v87
	v_mul_f32_e32 v214, v81, v81
	v_mul_f32_e32 v215, v83, v83
	v_fmac_f32_e32 v208, v92, v92
	v_fmac_f32_e32 v209, v94, v94
	v_fmac_f32_e32 v210, v88, v88
	v_fmac_f32_e32 v211, v90, v90
	v_fmac_f32_e32 v212, v84, v84
	v_fmac_f32_e32 v213, v86, v86
	v_fmac_f32_e32 v214, v80, v80
	v_fmac_f32_e32 v215, v82, v82
	v_add_f32_e32 v208, v208, v209
	v_add_f32_e32 v210, v210, v211
	v_add_f32_e32 v212, v212, v213
	v_add_f32_e32 v208, v208, v210
	v_add_f32_e32 v208, v208, v212
	v_add_f32_e32 v214, v214, v215
	v_add_f32_e32 v148, v208, v214
	ds_bpermute_b32 v156, v144, v148
	s_add_u32 s100, s16, 0xb0000
	s_addc_u32 s101, s17, 0
	s_add_u32 s44, s16, 0xb8000
	s_addc_u32 s45, s17, 0
	global_load_dwordx4 v[208:211], v142, s[100:101] nt
	global_load_dwordx4 v[212:215], v142, s[44:45] nt
	global_load_dwordx4 v[216:219], v142, s[100:101] offset:512 nt
	global_load_dwordx4 v[220:223], v142, s[44:45] offset:512 nt
	s_waitcnt vmcnt(16)
	ds_write_b128 v172, v[224:227]
	ds_write_b128 v172, v[228:231] offset:1152
	ds_read_b128 v[224:227], v171
	ds_read_b128 v[228:231], v171 offset:64
	ds_write_b128 v172, v[232:235]
	ds_write_b128 v172, v[236:239] offset:1152
	ds_read_b128 v[232:235], v171
	ds_read_b128 v[236:239], v171 offset:64
	s_waitcnt lgkmcnt(0)
	v_pk_add_f32 v[76:77], v[76:77], v[224:225]
	v_pk_add_f32 v[78:79], v[78:79], v[226:227]
	v_pk_add_f32 v[72:73], v[72:73], v[228:229]
	v_pk_add_f32 v[74:75], v[74:75], v[230:231]
	v_pk_add_f32 v[68:69], v[68:69], v[232:233]
	v_pk_add_f32 v[70:71], v[70:71], v[234:235]
	v_pk_add_f32 v[64:65], v[64:65], v[236:237]
	v_pk_add_f32 v[66:67], v[66:67], v[238:239]
	v_mul_f32_e32 v224, v77, v77
	v_mul_f32_e32 v225, v79, v79
	v_mul_f32_e32 v226, v73, v73
	v_mul_f32_e32 v227, v75, v75
	v_mul_f32_e32 v228, v69, v69
	v_mul_f32_e32 v229, v71, v71
	v_mul_f32_e32 v230, v65, v65
	v_mul_f32_e32 v231, v67, v67
	v_fmac_f32_e32 v224, v76, v76
	v_fmac_f32_e32 v225, v78, v78
	v_fmac_f32_e32 v226, v72, v72
	v_fmac_f32_e32 v227, v74, v74
	v_fmac_f32_e32 v228, v68, v68
	v_fmac_f32_e32 v229, v70, v70
	v_fmac_f32_e32 v230, v64, v64
	v_fmac_f32_e32 v231, v66, v66
	v_add_f32_e32 v224, v224, v225
	v_add_f32_e32 v226, v226, v227
	v_add_f32_e32 v228, v228, v229
	v_add_f32_e32 v224, v224, v226
	v_add_f32_e32 v224, v224, v228
	v_add_f32_e32 v230, v230, v231
	v_add_f32_e32 v149, v224, v230
	ds_bpermute_b32 v157, v144, v149
	s_waitcnt vmcnt(12)
	ds_write_b128 v172, v[240:243]
	ds_write_b128 v172, v[244:247] offset:1152
	ds_read_b128 v[240:243], v171
	ds_read_b128 v[244:247], v171 offset:64
	ds_write_b128 v172, v[248:251]
	ds_write_b128 v172, v[252:255] offset:1152
	ds_read_b128 v[248:251], v171
	ds_read_b128 v[252:255], v171 offset:64
	s_waitcnt lgkmcnt(0)
	v_pk_add_f32 v[60:61], v[60:61], v[240:241]
	v_pk_add_f32 v[62:63], v[62:63], v[242:243]
	v_pk_add_f32 v[56:57], v[56:57], v[244:245]
	v_pk_add_f32 v[58:59], v[58:59], v[246:247]
	v_pk_add_f32 v[52:53], v[52:53], v[248:249]
	v_pk_add_f32 v[54:55], v[54:55], v[250:251]
	v_pk_add_f32 v[48:49], v[48:49], v[252:253]
	v_pk_add_f32 v[50:51], v[50:51], v[254:255]
	v_mul_f32_e32 v240, v61, v61
	v_mul_f32_e32 v241, v63, v63
	v_mul_f32_e32 v242, v57, v57
	v_mul_f32_e32 v243, v59, v59
	v_mul_f32_e32 v244, v53, v53
	v_mul_f32_e32 v245, v55, v55
	v_mul_f32_e32 v246, v49, v49
	v_mul_f32_e32 v247, v51, v51
	v_fmac_f32_e32 v240, v60, v60
	v_fmac_f32_e32 v241, v62, v62
	v_fmac_f32_e32 v242, v56, v56
	v_fmac_f32_e32 v243, v58, v58
	v_fmac_f32_e32 v244, v52, v52
	v_fmac_f32_e32 v245, v54, v54
	v_fmac_f32_e32 v246, v48, v48
	v_fmac_f32_e32 v247, v50, v50
	v_add_f32_e32 v240, v240, v241
	v_add_f32_e32 v242, v242, v243
	v_add_f32_e32 v244, v244, v245
	v_add_f32_e32 v240, v240, v242
	v_add_f32_e32 v240, v240, v244
	v_add_f32_e32 v246, v246, v247
	v_add_f32_e32 v150, v240, v246
	ds_bpermute_b32 v158, v144, v150
	s_waitcnt vmcnt(8)
	ds_write_b128 v172, v[176:179]
	ds_write_b128 v172, v[180:183] offset:1152
	ds_read_b128 v[176:179], v171
	ds_read_b128 v[180:183], v171 offset:64
	ds_write_b128 v172, v[184:187]
	ds_write_b128 v172, v[188:191] offset:1152
	ds_read_b128 v[184:187], v171
	ds_read_b128 v[188:191], v171 offset:64
	s_waitcnt lgkmcnt(0)
	v_pk_add_f32 v[44:45], v[44:45], v[176:177]
	v_pk_add_f32 v[46:47], v[46:47], v[178:179]
	v_pk_add_f32 v[40:41], v[40:41], v[180:181]
	v_pk_add_f32 v[42:43], v[42:43], v[182:183]
	v_pk_add_f32 v[36:37], v[36:37], v[184:185]
	v_pk_add_f32 v[38:39], v[38:39], v[186:187]
	v_pk_add_f32 v[32:33], v[32:33], v[188:189]
	v_pk_add_f32 v[34:35], v[34:35], v[190:191]
	v_mul_f32_e32 v176, v45, v45
	v_mul_f32_e32 v177, v47, v47
	v_mul_f32_e32 v178, v41, v41
	v_mul_f32_e32 v179, v43, v43
	v_mul_f32_e32 v180, v37, v37
	v_mul_f32_e32 v181, v39, v39
	v_mul_f32_e32 v182, v33, v33
	v_mul_f32_e32 v183, v35, v35
	v_fmac_f32_e32 v176, v44, v44
	v_fmac_f32_e32 v177, v46, v46
	v_fmac_f32_e32 v178, v40, v40
	v_fmac_f32_e32 v179, v42, v42
	v_fmac_f32_e32 v180, v36, v36
	v_fmac_f32_e32 v181, v38, v38
	v_fmac_f32_e32 v182, v32, v32
	v_fmac_f32_e32 v183, v34, v34
	v_add_f32_e32 v176, v176, v177
	v_add_f32_e32 v178, v178, v179
	v_add_f32_e32 v180, v180, v181
	v_add_f32_e32 v176, v176, v178
	v_add_f32_e32 v176, v176, v180
	v_add_f32_e32 v182, v182, v183
	v_add_f32_e32 v151, v176, v182
	ds_bpermute_b32 v159, v144, v151
	s_waitcnt vmcnt(4)
	ds_write_b128 v172, v[192:195]
	ds_write_b128 v172, v[196:199] offset:1152
	ds_read_b128 v[192:195], v171
	ds_read_b128 v[196:199], v171 offset:64
	ds_write_b128 v172, v[200:203]
	ds_write_b128 v172, v[204:207] offset:1152
	ds_read_b128 v[200:203], v171
	ds_read_b128 v[204:207], v171 offset:64
	s_waitcnt lgkmcnt(0)
	v_pk_add_f32 v[28:29], v[28:29], v[192:193]
	v_pk_add_f32 v[30:31], v[30:31], v[194:195]
	v_pk_add_f32 v[24:25], v[24:25], v[196:197]
	v_pk_add_f32 v[26:27], v[26:27], v[198:199]
	v_pk_add_f32 v[20:21], v[20:21], v[200:201]
	v_pk_add_f32 v[22:23], v[22:23], v[202:203]
	v_pk_add_f32 v[16:17], v[16:17], v[204:205]
	v_pk_add_f32 v[18:19], v[18:19], v[206:207]
	v_mul_f32_e32 v192, v29, v29
	v_mul_f32_e32 v193, v31, v31
	v_mul_f32_e32 v194, v25, v25
	v_mul_f32_e32 v195, v27, v27
	v_mul_f32_e32 v196, v21, v21
	v_mul_f32_e32 v197, v23, v23
	v_mul_f32_e32 v198, v17, v17
	v_mul_f32_e32 v199, v19, v19
	v_fmac_f32_e32 v192, v28, v28
	v_fmac_f32_e32 v193, v30, v30
	v_fmac_f32_e32 v194, v24, v24
	v_fmac_f32_e32 v195, v26, v26
	v_fmac_f32_e32 v196, v20, v20
	v_fmac_f32_e32 v197, v22, v22
	v_fmac_f32_e32 v198, v16, v16
	v_fmac_f32_e32 v199, v18, v18
	v_add_f32_e32 v192, v192, v193
	v_add_f32_e32 v194, v194, v195
	v_add_f32_e32 v196, v196, v197
	v_add_f32_e32 v192, v192, v194
	v_add_f32_e32 v192, v192, v196
	v_add_f32_e32 v198, v198, v199
	v_add_f32_e32 v152, v192, v198
	ds_bpermute_b32 v160, v144, v152
	s_waitcnt vmcnt(0)
	ds_write_b128 v172, v[208:211]
	ds_write_b128 v172, v[212:215] offset:1152
	ds_read_b128 v[208:211], v171
	ds_read_b128 v[212:215], v171 offset:64
	ds_write_b128 v172, v[216:219]
	ds_write_b128 v172, v[220:223] offset:1152
	ds_read_b128 v[216:219], v171
	ds_read_b128 v[220:223], v171 offset:64
	s_waitcnt lgkmcnt(0)
	v_pk_add_f32 v[12:13], v[12:13], v[208:209]
	v_pk_add_f32 v[14:15], v[14:15], v[210:211]
	v_pk_add_f32 v[8:9], v[8:9], v[212:213]
	v_pk_add_f32 v[10:11], v[10:11], v[214:215]
	v_pk_add_f32 v[4:5], v[4:5], v[216:217]
	v_pk_add_f32 v[6:7], v[6:7], v[218:219]
	v_pk_add_f32 v[0:1], v[0:1], v[220:221]
	v_pk_add_f32 v[2:3], v[2:3], v[222:223]
	v_mul_f32_e32 v208, v13, v13
	v_mul_f32_e32 v209, v15, v15
	v_mul_f32_e32 v210, v9, v9
	v_mul_f32_e32 v211, v11, v11
	v_mul_f32_e32 v212, v5, v5
	v_mul_f32_e32 v213, v7, v7
	v_mul_f32_e32 v214, v1, v1
	v_mul_f32_e32 v215, v3, v3
	v_fmac_f32_e32 v208, v12, v12
	v_fmac_f32_e32 v209, v14, v14
	v_fmac_f32_e32 v210, v8, v8
	v_fmac_f32_e32 v211, v10, v10
	v_fmac_f32_e32 v212, v4, v4
	v_fmac_f32_e32 v213, v6, v6
	v_fmac_f32_e32 v214, v0, v0
	v_fmac_f32_e32 v215, v2, v2
	v_add_f32_e32 v208, v208, v209
	v_add_f32_e32 v210, v210, v211
	v_add_f32_e32 v212, v212, v213
	v_add_f32_e32 v208, v208, v210
	v_add_f32_e32 v208, v208, v212
	v_add_f32_e32 v214, v214, v215
	v_add_f32_e32 v153, v208, v214
	ds_bpermute_b32 v161, v144, v153
	s_waitcnt lgkmcnt(0)
	v_add_f32_e32 v146, v146, v154
	v_add_f32_e32 v147, v147, v155
	v_add_f32_e32 v148, v148, v156
	v_add_f32_e32 v149, v149, v157
	v_add_f32_e32 v150, v150, v158
	v_add_f32_e32 v151, v151, v159
	v_add_f32_e32 v152, v152, v160
	v_add_f32_e32 v153, v153, v161
	ds_bpermute_b32 v154, v145, v146
	ds_bpermute_b32 v155, v145, v147
	ds_bpermute_b32 v156, v145, v148
	ds_bpermute_b32 v157, v145, v149
	ds_bpermute_b32 v158, v145, v150
	ds_bpermute_b32 v159, v145, v151
	ds_bpermute_b32 v160, v145, v152
	ds_bpermute_b32 v161, v145, v153
	s_and_saveexec_b64 s[42:43], s[0:1]
	s_waitcnt lgkmcnt(0)
	v_add_f32_e32 v146, v146, v154
	v_add_f32_e32 v147, v147, v155
	v_add_f32_e32 v148, v148, v156
	v_add_f32_e32 v149, v149, v157
	v_add_f32_e32 v150, v150, v158
	v_add_f32_e32 v151, v151, v159
	v_add_f32_e32 v152, v152, v160
	v_add_f32_e32 v153, v153, v161
	global_atomic_add_f32 v141, v146, s[10:11]
	global_atomic_add_f32 v141, v147, s[10:11] offset:64
	global_atomic_add_f32 v141, v148, s[10:11] offset:128
	global_atomic_add_f32 v141, v149, s[10:11] offset:192
	global_atomic_add_f32 v141, v150, s[10:11] offset:512
	global_atomic_add_f32 v141, v151, s[10:11] offset:576
	global_atomic_add_f32 v141, v152, s[10:11] offset:640
	global_atomic_add_f32 v141, v153, s[10:11] offset:704
	s_or_b64 exec, exec, s[42:43]
	global_load_dwordx4 v[176:179], v143, s[12:13]
	global_load_dwordx4 v[180:183], v143, s[12:13] offset:64
	global_load_dwordx4 v[184:187], v143, s[12:13] offset:512
	global_load_dwordx4 v[188:191], v143, s[12:13] offset:576
	s_lshl_b32 s8, s8, 7
	s_add_i32 s8, s8, s59
	s_ashr_i32 s9, s8, 31
	s_waitcnt vmcnt(0)
	s_lshl_b64 s[8:9], s[8:9], 2
	s_add_u32 s8, s64, s8
	s_addc_u32 s9, s65, s9
	s_and_saveexec_b64 s[42:43], s[4:5]
	s_cbranch_execz .LBB0_507
	s_mov_b64 s[44:45], exec
	v_mbcnt_lo_u32_b32 v160, s44, 0
	v_mbcnt_hi_u32_b32 v160, s45, v160
	v_cmp_eq_u32_e32 vcc, 0, v160
	s_and_b64 s[46:47], exec, vcc
	s_mov_b64 exec, s[46:47]
	s_cbranch_execz .LBB0_507
	s_bcnt1_i32_b64 s35, s[44:45]
	v_mov_b32_e32 v160, s35
	global_atomic_add v129, v160, s[8:9]

.LBB0_515:
	global_load_dword v192, v141, s[10:11] sc1
	global_load_dword v193, v141, s[10:11] offset:64 sc1
	global_load_dword v194, v141, s[10:11] offset:128 sc1
	global_load_dword v195, v141, s[10:11] offset:192 sc1
	global_load_dword v196, v141, s[10:11] offset:512 sc1
	global_load_dword v197, v141, s[10:11] offset:576 sc1
	global_load_dword v198, v141, s[10:11] offset:640 sc1
	global_load_dword v199, v141, s[10:11] offset:704 sc1
	s_waitcnt vmcnt(0)
	v_fmamk_f32 v192, v192, 0x3a800000, v169
	v_mul_f32_e32 v200, 0x4f800000, v192
	v_cmp_gt_f32_e32 vcc, s68, v192
	s_nop 1
	v_cndmask_b32_e32 v192, v192, v200, vcc
	v_sqrt_f32_e32 v200, v192
	s_nop 0
	v_add_u32_e32 v201, -1, v200
	v_add_u32_e32 v202, 1, v200
	v_fma_f32 v203, -v201, v200, v192
	v_fma_f32 v204, -v202, v200, v192
	v_cmp_ge_f32_e64 s[8:9], 0, v203
	s_nop 1
	v_cndmask_b32_e64 v200, v200, v201, s[8:9]
	v_cmp_lt_f32_e64 s[8:9], 0, v204
	s_nop 1
	v_cndmask_b32_e64 v200, v200, v202, s[8:9]
	v_mul_f32_e32 v201, 0x37800000, v200
	v_cndmask_b32_e32 v200, v200, v201, vcc
	v_cmp_class_f32_e32 vcc, v192, v170
	s_nop 1
	v_cndmask_b32_e32 v192, v200, v192, vcc
	v_div_scale_f32 v202, s[8:9], v192, v192, 1.0
	v_rcp_f32_e32 v203, v202
	v_div_scale_f32 v200, vcc, 1.0, v192, 1.0
	v_fma_f32 v201, -v202, v203, 1.0
	v_fmac_f32_e32 v203, v201, v203
	v_mul_f32_e32 v201, v200, v203
	v_fma_f32 v204, -v202, v201, v200
	v_fmac_f32_e32 v201, v204, v203
	v_fma_f32 v200, -v202, v201, v200
	v_div_fmas_f32 v200, v200, v203, v201
	v_div_fixup_f32 v206, v200, v192, 1.0
	v_pk_mul_f32 v[124:125], v[124:125], v[206:207] op_sel_hi:[1,0]
	v_pk_mul_f32 v[126:127], v[126:127], v[206:207] op_sel_hi:[1,0]
	v_pk_mul_f32 v[124:125], v[176:177], v[124:125]
	v_pk_mul_f32 v[126:127], v[178:179], v[126:127]
	v_pk_mul_f32 v[120:121], v[120:121], v[206:207] op_sel_hi:[1,0]
	v_pk_mul_f32 v[122:123], v[122:123], v[206:207] op_sel_hi:[1,0]
	v_pk_mul_f32 v[120:121], v[180:181], v[120:121]
	v_pk_mul_f32 v[122:123], v[182:183], v[122:123]
	v_pk_mul_f32 v[116:117], v[116:117], v[206:207] op_sel_hi:[1,0]
	v_pk_mul_f32 v[118:119], v[118:119], v[206:207] op_sel_hi:[1,0]
	v_pk_mul_f32 v[116:117], v[184:185], v[116:117]
	v_pk_mul_f32 v[118:119], v[186:187], v[118:119]
	v_pk_mul_f32 v[112:113], v[112:113], v[206:207] op_sel_hi:[1,0]
	v_pk_mul_f32 v[114:115], v[114:115], v[206:207] op_sel_hi:[1,0]
	v_pk_mul_f32 v[112:113], v[188:189], v[112:113]
	v_pk_mul_f32 v[114:115], v[190:191], v[114:115]
	ds_write_b128 v171, v[124:127]
	ds_write_b128 v171, v[120:123] offset:64
	ds_read_b128 v[124:127], v172
	ds_read_b128 v[120:123], v172 offset:1152
	ds_write_b128 v171, v[116:119]
	ds_write_b128 v171, v[112:115] offset:64
	ds_read_b128 v[116:119], v172
	ds_read_b128 v[112:115], v172 offset:1152
	s_add_u32 s100, s14, 0x0
	s_addc_u32 s101, s15, 0
	s_add_u32 s44, s14, 0x8000
	s_addc_u32 s45, s15, 0
	s_waitcnt lgkmcnt(4)
	global_store_dwordx4 v142, v[124:127], s[100:101] nt
	global_store_dwordx4 v142, v[120:123], s[44:45] nt
	s_waitcnt lgkmcnt(0)
	global_store_dwordx4 v142, v[116:119], s[100:101] offset:512 nt
	global_store_dwordx4 v142, v[112:115], s[44:45] offset:512 nt
	v_fmamk_f32 v193, v193, 0x3a800000, v169
	v_mul_f32_e32 v200, 0x4f800000, v193
	v_cmp_gt_f32_e32 vcc, s68, v193
	s_nop 1
	v_cndmask_b32_e32 v193, v193, v200, vcc
	v_sqrt_f32_e32 v200, v193
	s_nop 0
	v_add_u32_e32 v201, -1, v200
	v_add_u32_e32 v202, 1, v200
	v_fma_f32 v203, -v201, v200, v193
	v_fma_f32 v204, -v202, v200, v193
	v_cmp_ge_f32_e64 s[8:9], 0, v203
	s_nop 1
	v_cndmask_b32_e64 v200, v200, v201, s[8:9]
	v_cmp_lt_f32_e64 s[8:9], 0, v204
	s_nop 1
	v_cndmask_b32_e64 v200, v200, v202, s[8:9]
	v_mul_f32_e32 v201, 0x37800000, v200
	v_cndmask_b32_e32 v200, v200, v201, vcc
	v_cmp_class_f32_e32 vcc, v193, v170
	s_nop 1
	v_cndmask_b32_e32 v193, v200, v193, vcc
	v_div_scale_f32 v202, s[8:9], v193, v193, 1.0
	v_rcp_f32_e32 v203, v202
	v_div_scale_f32 v200, vcc, 1.0, v193, 1.0
	v_fma_f32 v201, -v202, v203, 1.0
	v_fmac_f32_e32 v203, v201, v203
	v_mul_f32_e32 v201, v200, v203
	v_fma_f32 v204, -v202, v201, v200
	v_fmac_f32_e32 v201, v204, v203
	v_fma_f32 v200, -v202, v201, v200
	v_div_fmas_f32 v200, v200, v203, v201
	v_div_fixup_f32 v206, v200, v193, 1.0
	v_pk_mul_f32 v[108:109], v[108:109], v[206:207] op_sel_hi:[1,0]
	v_pk_mul_f32 v[110:111], v[110:111], v[206:207] op_sel_hi:[1,0]
	v_pk_mul_f32 v[108:109], v[176:177], v[108:109]
	v_pk_mul_f32 v[110:111], v[178:179], v[110:111]
	v_pk_mul_f32 v[104:105], v[104:105], v[206:207] op_sel_hi:[1,0]
	v_pk_mul_f32 v[106:107], v[106:107], v[206:207] op_sel_hi:[1,0]
	v_pk_mul_f32 v[104:105], v[180:181], v[104:105]
	v_pk_mul_f32 v[106:107], v[182:183], v[106:107]
	v_pk_mul_f32 v[100:101], v[100:101], v[206:207] op_sel_hi:[1,0]
	v_pk_mul_f32 v[102:103], v[102:103], v[206:207] op_sel_hi:[1,0]
	v_pk_mul_f32 v[100:101], v[184:185], v[100:101]
	v_pk_mul_f32 v[102:103], v[186:187], v[102:103]
	v_pk_mul_f32 v[96:97], v[96:97], v[206:207] op_sel_hi:[1,0]
	v_pk_mul_f32 v[98:99], v[98:99], v[206:207] op_sel_hi:[1,0]
	v_pk_mul_f32 v[96:97], v[188:189], v[96:97]
	v_pk_mul_f32 v[98:99], v[190:191], v[98:99]
	ds_write_b128 v171, v[108:111]
	ds_write_b128 v171, v[104:107] offset:64
	ds_read_b128 v[108:111], v172
	ds_read_b128 v[104:107], v172 offset:1152
	ds_write_b128 v171, v[100:103]
	ds_write_b128 v171, v[96:99] offset:64
	ds_read_b128 v[100:103], v172
	ds_read_b128 v[96:99], v172 offset:1152
	s_add_u32 s100, s14, 0x10000
	s_addc_u32 s101, s15, 0
	s_add_u32 s44, s14, 0x18000
	s_addc_u32 s45, s15, 0
	s_waitcnt lgkmcnt(4)
	global_store_dwordx4 v142, v[108:111], s[100:101] nt
	global_store_dwordx4 v142, v[104:107], s[44:45] nt
	s_waitcnt lgkmcnt(0)
	global_store_dwordx4 v142, v[100:103], s[100:101] offset:512 nt
	global_store_dwordx4 v142, v[96:99], s[44:45] offset:512 nt
	v_fmamk_f32 v194, v194, 0x3a800000, v169
	v_mul_f32_e32 v200, 0x4f800000, v194
	v_cmp_gt_f32_e32 vcc, s68, v194
	s_nop 1
	v_cndmask_b32_e32 v194, v194, v200, vcc
	v_sqrt_f32_e32 v200, v194
	s_nop 0
	v_add_u32_e32 v201, -1, v200
	v_add_u32_e32 v202, 1, v200
	v_fma_f32 v203, -v201, v200, v194
	v_fma_f32 v204, -v202, v200, v194
	v_cmp_ge_f32_e64 s[8:9], 0, v203
	s_nop 1
	v_cndmask_b32_e64 v200, v200, v201, s[8:9]
	v_cmp_lt_f32_e64 s[8:9], 0, v204
	s_nop 1
	v_cndmask_b32_e64 v200, v200, v202, s[8:9]
	v_mul_f32_e32 v201, 0x37800000, v200
	v_cndmask_b32_e32 v200, v200, v201, vcc
	v_cmp_class_f32_e32 vcc, v194, v170
	s_nop 1
	v_cndmask_b32_e32 v194, v200, v194, vcc
	v_div_scale_f32 v202, s[8:9], v194, v194, 1.0
	v_rcp_f32_e32 v203, v202
	v_div_scale_f32 v200, vcc, 1.0, v194, 1.0
	v_fma_f32 v201, -v202, v203, 1.0
	v_fmac_f32_e32 v203, v201, v203
	v_mul_f32_e32 v201, v200, v203
	v_fma_f32 v204, -v202, v201, v200
	v_fmac_f32_e32 v201, v204, v203
	v_fma_f32 v200, -v202, v201, v200
	v_div_fmas_f32 v200, v200, v203, v201
	v_div_fixup_f32 v206, v200, v194, 1.0
	v_pk_mul_f32 v[92:93], v[92:93], v[206:207] op_sel_hi:[1,0]
	v_pk_mul_f32 v[94:95], v[94:95], v[206:207] op_sel_hi:[1,0]
	v_pk_mul_f32 v[92:93], v[176:177], v[92:93]
	v_pk_mul_f32 v[94:95], v[178:179], v[94:95]
	v_pk_mul_f32 v[88:89], v[88:89], v[206:207] op_sel_hi:[1,0]
	v_pk_mul_f32 v[90:91], v[90:91], v[206:207] op_sel_hi:[1,0]
	v_pk_mul_f32 v[88:89], v[180:181], v[88:89]
	v_pk_mul_f32 v[90:91], v[182:183], v[90:91]
	v_pk_mul_f32 v[84:85], v[84:85], v[206:207] op_sel_hi:[1,0]
	v_pk_mul_f32 v[86:87], v[86:87], v[206:207] op_sel_hi:[1,0]
	v_pk_mul_f32 v[84:85], v[184:185], v[84:85]
	v_pk_mul_f32 v[86:87], v[186:187], v[86:87]
	v_pk_mul_f32 v[80:81], v[80:81], v[206:207] op_sel_hi:[1,0]
	v_pk_mul_f32 v[82:83], v[82:83], v[206:207] op_sel_hi:[1,0]
	v_pk_mul_f32 v[80:81], v[188:189], v[80:81]
	v_pk_mul_f32 v[82:83], v[190:191], v[82:83]
	ds_write_b128 v171, v[92:95]
	ds_write_b128 v171, v[88:91] offset:64
	ds_read_b128 v[92:95], v172
	ds_read_b128 v[88:91], v172 offset:1152
	ds_write_b128 v171, v[84:87]
	ds_write_b128 v171, v[80:83] offset:64
	ds_read_b128 v[84:87], v172
	ds_read_b128 v[80:83], v172 offset:1152
	s_add_u32 s100, s14, 0x20000
	s_addc_u32 s101, s15, 0
	s_add_u32 s44, s14, 0x28000
	s_addc_u32 s45, s15, 0
	s_waitcnt lgkmcnt(4)
	global_store_dwordx4 v142, v[92:95], s[100:101] nt
	global_store_dwordx4 v142, v[88:91], s[44:45] nt
	s_waitcnt lgkmcnt(0)
	global_store_dwordx4 v142, v[84:87], s[100:101] offset:512 nt
	global_store_dwordx4 v142, v[80:83], s[44:45] offset:512 nt
	v_fmamk_f32 v195, v195, 0x3a800000, v169
	v_mul_f32_e32 v200, 0x4f800000, v195
	v_cmp_gt_f32_e32 vcc, s68, v195
	s_nop 1
	v_cndmask_b32_e32 v195, v195, v200, vcc
	v_sqrt_f32_e32 v200, v195
	s_nop 0
	v_add_u32_e32 v201, -1, v200
	v_add_u32_e32 v202, 1, v200
	v_fma_f32 v203, -v201, v200, v195
	v_fma_f32 v204, -v202, v200, v195
	v_cmp_ge_f32_e64 s[8:9], 0, v203
	s_nop 1
	v_cndmask_b32_e64 v200, v200, v201, s[8:9]
	v_cmp_lt_f32_e64 s[8:9], 0, v204
	s_nop 1
	v_cndmask_b32_e64 v200, v200, v202, s[8:9]
	v_mul_f32_e32 v201, 0x37800000, v200
	v_cndmask_b32_e32 v200, v200, v201, vcc
	v_cmp_class_f32_e32 vcc, v195, v170
	s_nop 1
	v_cndmask_b32_e32 v195, v200, v195, vcc
	v_div_scale_f32 v202, s[8:9], v195, v195, 1.0
	v_rcp_f32_e32 v203, v202
	v_div_scale_f32 v200, vcc, 1.0, v195, 1.0
	v_fma_f32 v201, -v202, v203, 1.0
	v_fmac_f32_e32 v203, v201, v203
	v_mul_f32_e32 v201, v200, v203
	v_fma_f32 v204, -v202, v201, v200
	v_fmac_f32_e32 v201, v204, v203
	v_fma_f32 v200, -v202, v201, v200
	v_div_fmas_f32 v200, v200, v203, v201
	v_div_fixup_f32 v206, v200, v195, 1.0
	v_pk_mul_f32 v[76:77], v[76:77], v[206:207] op_sel_hi:[1,0]
	v_pk_mul_f32 v[78:79], v[78:79], v[206:207] op_sel_hi:[1,0]
	v_pk_mul_f32 v[76:77], v[176:177], v[76:77]
	v_pk_mul_f32 v[78:79], v[178:179], v[78:79]
	v_pk_mul_f32 v[72:73], v[72:73], v[206:207] op_sel_hi:[1,0]
	v_pk_mul_f32 v[74:75], v[74:75], v[206:207] op_sel_hi:[1,0]
	v_pk_mul_f32 v[72:73], v[180:181], v[72:73]
	v_pk_mul_f32 v[74:75], v[182:183], v[74:75]
	v_pk_mul_f32 v[68:69], v[68:69], v[206:207] op_sel_hi:[1,0]
	v_pk_mul_f32 v[70:71], v[70:71], v[206:207] op_sel_hi:[1,0]
	v_pk_mul_f32 v[68:69], v[184:185], v[68:69]
	v_pk_mul_f32 v[70:71], v[186:187], v[70:71]
	v_pk_mul_f32 v[64:65], v[64:65], v[206:207] op_sel_hi:[1,0]
	v_pk_mul_f32 v[66:67], v[66:67], v[206:207] op_sel_hi:[1,0]
	v_pk_mul_f32 v[64:65], v[188:189], v[64:65]
	v_pk_mul_f32 v[66:67], v[190:191], v[66:67]
	ds_write_b128 v171, v[76:79]
	ds_write_b128 v171, v[72:75] offset:64
	ds_read_b128 v[76:79], v172
	ds_read_b128 v[72:75], v172 offset:1152
	ds_write_b128 v171, v[68:71]
	ds_write_b128 v171, v[64:67] offset:64
	ds_read_b128 v[68:71], v172
	ds_read_b128 v[64:67], v172 offset:1152
	s_add_u32 s100, s14, 0x30000
	s_addc_u32 s101, s15, 0
	s_add_u32 s44, s14, 0x38000
	s_addc_u32 s45, s15, 0
	s_waitcnt lgkmcnt(4)
	global_store_dwordx4 v142, v[76:79], s[100:101] nt
	global_store_dwordx4 v142, v[72:75], s[44:45] nt
	s_waitcnt lgkmcnt(0)
	global_store_dwordx4 v142, v[68:71], s[100:101] offset:512 nt
	global_store_dwordx4 v142, v[64:67], s[44:45] offset:512 nt
	v_fmamk_f32 v196, v196, 0x3a800000, v169
	v_mul_f32_e32 v200, 0x4f800000, v196
	v_cmp_gt_f32_e32 vcc, s68, v196
	s_nop 1
	v_cndmask_b32_e32 v196, v196, v200, vcc
	v_sqrt_f32_e32 v200, v196
	s_nop 0
	v_add_u32_e32 v201, -1, v200
	v_add_u32_e32 v202, 1, v200
	v_fma_f32 v203, -v201, v200, v196
	v_fma_f32 v204, -v202, v200, v196
	v_cmp_ge_f32_e64 s[8:9], 0, v203
	s_nop 1
	v_cndmask_b32_e64 v200, v200, v201, s[8:9]
	v_cmp_lt_f32_e64 s[8:9], 0, v204
	s_nop 1
	v_cndmask_b32_e64 v200, v200, v202, s[8:9]
	v_mul_f32_e32 v201, 0x37800000, v200
	v_cndmask_b32_e32 v200, v200, v201, vcc
	v_cmp_class_f32_e32 vcc, v196, v170
	s_nop 1
	v_cndmask_b32_e32 v196, v200, v196, vcc
	v_div_scale_f32 v202, s[8:9], v196, v196, 1.0
	v_rcp_f32_e32 v203, v202
	v_div_scale_f32 v200, vcc, 1.0, v196, 1.0
	v_fma_f32 v201, -v202, v203, 1.0
	v_fmac_f32_e32 v203, v201, v203
	v_mul_f32_e32 v201, v200, v203
	v_fma_f32 v204, -v202, v201, v200
	v_fmac_f32_e32 v201, v204, v203
	v_fma_f32 v200, -v202, v201, v200
	v_div_fmas_f32 v200, v200, v203, v201
	v_div_fixup_f32 v206, v200, v196, 1.0
	v_pk_mul_f32 v[60:61], v[60:61], v[206:207] op_sel_hi:[1,0]
	v_pk_mul_f32 v[62:63], v[62:63], v[206:207] op_sel_hi:[1,0]
	v_pk_mul_f32 v[60:61], v[176:177], v[60:61]
	v_pk_mul_f32 v[62:63], v[178:179], v[62:63]
	v_pk_mul_f32 v[56:57], v[56:57], v[206:207] op_sel_hi:[1,0]
	v_pk_mul_f32 v[58:59], v[58:59], v[206:207] op_sel_hi:[1,0]
	v_pk_mul_f32 v[56:57], v[180:181], v[56:57]
	v_pk_mul_f32 v[58:59], v[182:183], v[58:59]
	v_pk_mul_f32 v[52:53], v[52:53], v[206:207] op_sel_hi:[1,0]
	v_pk_mul_f32 v[54:55], v[54:55], v[206:207] op_sel_hi:[1,0]
	v_pk_mul_f32 v[52:53], v[184:185], v[52:53]
	v_pk_mul_f32 v[54:55], v[186:187], v[54:55]
	v_pk_mul_f32 v[48:49], v[48:49], v[206:207] op_sel_hi:[1,0]
	v_pk_mul_f32 v[50:51], v[50:51], v[206:207] op_sel_hi:[1,0]
	v_pk_mul_f32 v[48:49], v[188:189], v[48:49]
	v_pk_mul_f32 v[50:51], v[190:191], v[50:51]
	ds_write_b128 v171, v[60:63]
	ds_write_b128 v171, v[56:59] offset:64
	ds_read_b128 v[60:63], v172
	ds_read_b128 v[56:59], v172 offset:1152
	ds_write_b128 v171, v[52:55]
	ds_write_b128 v171, v[48:51] offset:64
	ds_read_b128 v[52:55], v172
	ds_read_b128 v[48:51], v172 offset:1152
	s_add_u32 s100, s14, 0x80000
	s_addc_u32 s101, s15, 0
	s_add_u32 s44, s14, 0x88000
	s_addc_u32 s45, s15, 0
	s_waitcnt lgkmcnt(4)
	global_store_dwordx4 v142, v[60:63], s[100:101] nt
	global_store_dwordx4 v142, v[56:59], s[44:45] nt
	s_waitcnt lgkmcnt(0)
	global_store_dwordx4 v142, v[52:55], s[100:101] offset:512 nt
	global_store_dwordx4 v142, v[48:51], s[44:45] offset:512 nt
	v_fmamk_f32 v197, v197, 0x3a800000, v169
	v_mul_f32_e32 v200, 0x4f800000, v197
	v_cmp_gt_f32_e32 vcc, s68, v197
	s_nop 1
	v_cndmask_b32_e32 v197, v197, v200, vcc
	v_sqrt_f32_e32 v200, v197
	s_nop 0
	v_add_u32_e32 v201, -1, v200
	v_add_u32_e32 v202, 1, v200
	v_fma_f32 v203, -v201, v200, v197
	v_fma_f32 v204, -v202, v200, v197
	v_cmp_ge_f32_e64 s[8:9], 0, v203
	s_nop 1
	v_cndmask_b32_e64 v200, v200, v201, s[8:9]
	v_cmp_lt_f32_e64 s[8:9], 0, v204
	s_nop 1
	v_cndmask_b32_e64 v200, v200, v202, s[8:9]
	v_mul_f32_e32 v201, 0x37800000, v200
	v_cndmask_b32_e32 v200, v200, v201, vcc
	v_cmp_class_f32_e32 vcc, v197, v170
	s_nop 1
	v_cndmask_b32_e32 v197, v200, v197, vcc
	v_div_scale_f32 v202, s[8:9], v197, v197, 1.0
	v_rcp_f32_e32 v203, v202
	v_div_scale_f32 v200, vcc, 1.0, v197, 1.0
	v_fma_f32 v201, -v202, v203, 1.0
	v_fmac_f32_e32 v203, v201, v203
	v_mul_f32_e32 v201, v200, v203
	v_fma_f32 v204, -v202, v201, v200
	v_fmac_f32_e32 v201, v204, v203
	v_fma_f32 v200, -v202, v201, v200
	v_div_fmas_f32 v200, v200, v203, v201
	v_div_fixup_f32 v206, v200, v197, 1.0
	v_pk_mul_f32 v[44:45], v[44:45], v[206:207] op_sel_hi:[1,0]
	v_pk_mul_f32 v[46:47], v[46:47], v[206:207] op_sel_hi:[1,0]
	v_pk_mul_f32 v[44:45], v[176:177], v[44:45]
	v_pk_mul_f32 v[46:47], v[178:179], v[46:47]
	v_pk_mul_f32 v[40:41], v[40:41], v[206:207] op_sel_hi:[1,0]
	v_pk_mul_f32 v[42:43], v[42:43], v[206:207] op_sel_hi:[1,0]
	v_pk_mul_f32 v[40:41], v[180:181], v[40:41]
	v_pk_mul_f32 v[42:43], v[182:183], v[42:43]
	v_pk_mul_f32 v[36:37], v[36:37], v[206:207] op_sel_hi:[1,0]
	v_pk_mul_f32 v[38:39], v[38:39], v[206:207] op_sel_hi:[1,0]
	v_pk_mul_f32 v[36:37], v[184:185], v[36:37]
	v_pk_mul_f32 v[38:39], v[186:187], v[38:39]
	v_pk_mul_f32 v[32:33], v[32:33], v[206:207] op_sel_hi:[1,0]
	v_pk_mul_f32 v[34:35], v[34:35], v[206:207] op_sel_hi:[1,0]
	v_pk_mul_f32 v[32:33], v[188:189], v[32:33]
	v_pk_mul_f32 v[34:35], v[190:191], v[34:35]
	ds_write_b128 v171, v[44:47]
	ds_write_b128 v171, v[40:43] offset:64
	ds_read_b128 v[44:47], v172
	ds_read_b128 v[40:43], v172 offset:1152
	ds_write_b128 v171, v[36:39]
	ds_write_b128 v171, v[32:35] offset:64
	ds_read_b128 v[36:39], v172
	ds_read_b128 v[32:35], v172 offset:1152
	s_add_u32 s100, s14, 0x90000
	s_addc_u32 s101, s15, 0
	s_add_u32 s44, s14, 0x98000
	s_addc_u32 s45, s15, 0
	s_waitcnt lgkmcnt(4)
	global_store_dwordx4 v142, v[44:47], s[100:101] nt
	global_store_dwordx4 v142, v[40:43], s[44:45] nt
	s_waitcnt lgkmcnt(0)
	global_store_dwordx4 v142, v[36:39], s[100:101] offset:512 nt
	global_store_dwordx4 v142, v[32:35], s[44:45] offset:512 nt
	v_fmamk_f32 v198, v198, 0x3a800000, v169
	v_mul_f32_e32 v200, 0x4f800000, v198
	v_cmp_gt_f32_e32 vcc, s68, v198
	s_nop 1
	v_cndmask_b32_e32 v198, v198, v200, vcc
	v_sqrt_f32_e32 v200, v198
	s_nop 0
	v_add_u32_e32 v201, -1, v200
	v_add_u32_e32 v202, 1, v200
	v_fma_f32 v203, -v201, v200, v198
	v_fma_f32 v204, -v202, v200, v198
	v_cmp_ge_f32_e64 s[8:9], 0, v203
	s_nop 1
	v_cndmask_b32_e64 v200, v200, v201, s[8:9]
	v_cmp_lt_f32_e64 s[8:9], 0, v204
	s_nop 1
	v_cndmask_b32_e64 v200, v200, v202, s[8:9]
	v_mul_f32_e32 v201, 0x37800000, v200
	v_cndmask_b32_e32 v200, v200, v201, vcc
	v_cmp_class_f32_e32 vcc, v198, v170
	s_nop 1
	v_cndmask_b32_e32 v198, v200, v198, vcc
	v_div_scale_f32 v202, s[8:9], v198, v198, 1.0
	v_rcp_f32_e32 v203, v202
	v_div_scale_f32 v200, vcc, 1.0, v198, 1.0
	v_fma_f32 v201, -v202, v203, 1.0
	v_fmac_f32_e32 v203, v201, v203
	v_mul_f32_e32 v201, v200, v203
	v_fma_f32 v204, -v202, v201, v200
	v_fmac_f32_e32 v201, v204, v203
	v_fma_f32 v200, -v202, v201, v200
	v_div_fmas_f32 v200, v200, v203, v201
	v_div_fixup_f32 v206, v200, v198, 1.0
	v_pk_mul_f32 v[28:29], v[28:29], v[206:207] op_sel_hi:[1,0]
	v_pk_mul_f32 v[30:31], v[30:31], v[206:207] op_sel_hi:[1,0]
	v_pk_mul_f32 v[28:29], v[176:177], v[28:29]
	v_pk_mul_f32 v[30:31], v[178:179], v[30:31]
	v_pk_mul_f32 v[24:25], v[24:25], v[206:207] op_sel_hi:[1,0]
	v_pk_mul_f32 v[26:27], v[26:27], v[206:207] op_sel_hi:[1,0]
	v_pk_mul_f32 v[24:25], v[180:181], v[24:25]
	v_pk_mul_f32 v[26:27], v[182:183], v[26:27]
	v_pk_mul_f32 v[20:21], v[20:21], v[206:207] op_sel_hi:[1,0]
	v_pk_mul_f32 v[22:23], v[22:23], v[206:207] op_sel_hi:[1,0]
	v_pk_mul_f32 v[20:21], v[184:185], v[20:21]
	v_pk_mul_f32 v[22:23], v[186:187], v[22:23]
	v_pk_mul_f32 v[16:17], v[16:17], v[206:207] op_sel_hi:[1,0]
	v_pk_mul_f32 v[18:19], v[18:19], v[206:207] op_sel_hi:[1,0]
	v_pk_mul_f32 v[16:17], v[188:189], v[16:17]
	v_pk_mul_f32 v[18:19], v[190:191], v[18:19]
	ds_write_b128 v171, v[28:31]
	ds_write_b128 v171, v[24:27] offset:64
	ds_read_b128 v[28:31], v172
	ds_read_b128 v[24:27], v172 offset:1152
	ds_write_b128 v171, v[20:23]
	ds_write_b128 v171, v[16:19] offset:64
	ds_read_b128 v[20:23], v172
	ds_read_b128 v[16:19], v172 offset:1152
	s_add_u32 s100, s14, 0xa0000
	s_addc_u32 s101, s15, 0
	s_add_u32 s44, s14, 0xa8000
	s_addc_u32 s45, s15, 0
	s_waitcnt lgkmcnt(4)
	global_store_dwordx4 v142, v[28:31], s[100:101] nt
	global_store_dwordx4 v142, v[24:27], s[44:45] nt
	s_waitcnt lgkmcnt(0)
	global_store_dwordx4 v142, v[20:23], s[100:101] offset:512 nt
	global_store_dwordx4 v142, v[16:19], s[44:45] offset:512 nt
	v_fmamk_f32 v199, v199, 0x3a800000, v169
	v_mul_f32_e32 v200, 0x4f800000, v199
	v_cmp_gt_f32_e32 vcc, s68, v199
	s_nop 1
	v_cndmask_b32_e32 v199, v199, v200, vcc
	v_sqrt_f32_e32 v200, v199
	s_nop 0
	v_add_u32_e32 v201, -1, v200
	v_add_u32_e32 v202, 1, v200
	v_fma_f32 v203, -v201, v200, v199
	v_fma_f32 v204, -v202, v200, v199
	v_cmp_ge_f32_e64 s[8:9], 0, v203
	s_nop 1
	v_cndmask_b32_e64 v200, v200, v201, s[8:9]
	v_cmp_lt_f32_e64 s[8:9], 0, v204
	s_nop 1
	v_cndmask_b32_e64 v200, v200, v202, s[8:9]
	v_mul_f32_e32 v201, 0x37800000, v200
	v_cndmask_b32_e32 v200, v200, v201, vcc
	v_cmp_class_f32_e32 vcc, v199, v170
	s_nop 1
	v_cndmask_b32_e32 v199, v200, v199, vcc
	v_div_scale_f32 v202, s[8:9], v199, v199, 1.0
	v_rcp_f32_e32 v203, v202
	v_div_scale_f32 v200, vcc, 1.0, v199, 1.0
	v_fma_f32 v201, -v202, v203, 1.0
	v_fmac_f32_e32 v203, v201, v203
	v_mul_f32_e32 v201, v200, v203
	v_fma_f32 v204, -v202, v201, v200
	v_fmac_f32_e32 v201, v204, v203
	v_fma_f32 v200, -v202, v201, v200
	v_div_fmas_f32 v200, v200, v203, v201
	v_div_fixup_f32 v206, v200, v199, 1.0
	v_pk_mul_f32 v[12:13], v[12:13], v[206:207] op_sel_hi:[1,0]
	v_pk_mul_f32 v[14:15], v[14:15], v[206:207] op_sel_hi:[1,0]
	v_pk_mul_f32 v[12:13], v[176:177], v[12:13]
	v_pk_mul_f32 v[14:15], v[178:179], v[14:15]
	v_pk_mul_f32 v[8:9], v[8:9], v[206:207] op_sel_hi:[1,0]
	v_pk_mul_f32 v[10:11], v[10:11], v[206:207] op_sel_hi:[1,0]
	v_pk_mul_f32 v[8:9], v[180:181], v[8:9]
	v_pk_mul_f32 v[10:11], v[182:183], v[10:11]
	v_pk_mul_f32 v[4:5], v[4:5], v[206:207] op_sel_hi:[1,0]
	v_pk_mul_f32 v[6:7], v[6:7], v[206:207] op_sel_hi:[1,0]
	v_pk_mul_f32 v[4:5], v[184:185], v[4:5]
	v_pk_mul_f32 v[6:7], v[186:187], v[6:7]
	v_pk_mul_f32 v[0:1], v[0:1], v[206:207] op_sel_hi:[1,0]
	v_pk_mul_f32 v[2:3], v[2:3], v[206:207] op_sel_hi:[1,0]
	v_pk_mul_f32 v[0:1], v[188:189], v[0:1]
	v_pk_mul_f32 v[2:3], v[190:191], v[2:3]
	ds_write_b128 v171, v[12:15]
	ds_write_b128 v171, v[8:11] offset:64
	ds_read_b128 v[12:15], v172
	ds_read_b128 v[8:11], v172 offset:1152
	ds_write_b128 v171, v[4:7]
	ds_write_b128 v171, v[0:3] offset:64
	ds_read_b128 v[4:7], v172
	ds_read_b128 v[0:3], v172 offset:1152
	s_add_u32 s100, s14, 0xb0000
	s_addc_u32 s101, s15, 0
	s_add_u32 s44, s14, 0xb8000
	s_addc_u32 s45, s15, 0
	s_waitcnt lgkmcnt(4)
	global_store_dwordx4 v142, v[12:15], s[100:101] nt
	global_store_dwordx4 v142, v[8:11], s[44:45] nt
	s_waitcnt lgkmcnt(0)
	global_store_dwordx4 v142, v[4:7], s[100:101] offset:512 nt
	global_store_dwordx4 v142, v[0:3], s[44:45] offset:512 nt
	s_andn2_b64 vcc, exec, s[6:7]
	s_mov_b64 s[6:7], -1
	s_cbranch_vccnz .LBB0_477
	s_andn2_b64 vcc, exec, s[20:21]
	s_cbranch_vccnz .LBB0_476
	s_barrier
	s_branch .LBB0_476
